# K/V projection as one 64x64 mini-tile per workgroup (all 256 workgroups, before step 0) instead of 16 full tiles on 16 workgroups, on top of the hand-written mixer pieces
# speedup vs baseline: 1.0030x; 1.0026x over previous
.Llbf_done:
	s_cmp_lg_u32 s100, 1
	s_cbranch_scc1 .Lkv_done
	v_readlane_b32 s0, v252, 0
	v_readlane_b32 s56, v252, 45
	v_readlane_b32 s57, v252, 46
	s_nop 0
	s_lshr_b32 s1, s0, 6
	s_and_b32 s4, s0, 63
	s_lshr_b32 s5, s1, 1
	s_and_b32 s10, s1, 1
	s_lshl_b32 s26, s5, 21
	s_add_u32 s28, s56, 0x300000
	s_addc_u32 s29, s57, 0
	s_add_u32 s28, s28, s26
	s_addc_u32 s29, s29, 0
	s_lshl_b32 s26, s5, 20
	s_add_u32 s30, s56, 0x4e00000
	s_addc_u32 s31, s57, 0
	s_add_u32 s30, s30, s26
	s_addc_u32 s31, s31, 0
	s_lshl_b32 s26, s5, 19
	s_cmp_eq_u32 s10, 0
	s_mov_b32 s27, 0x200000
	s_cselect_b32 s27, 0x100000, s27
	s_add_u32 s26, s26, s27
	s_add_u32 s36, s56, s26
	s_addc_u32 s37, s57, 0
	s_cmp_eq_u32 s10, 0
	s_cbranch_scc0 .Lkv_vtype
	s_mov_b64 s[44:45], s[28:29]
	s_mov_b64 s[46:47], s[30:31]
	s_movk_i32 s38, 0x200
	s_lshr_b32 s39, s4, 2
	s_and_b32 s48, s4, 3
	s_branch .Lkv_common

.LBB0_175:
	s_and_b32 s10, s54, 1
	s_cmp_eq_u32 s10, 0
	s_cselect_b64 s[4:5], -1, 0
	s_and_b64 s[0:1], s[4:5], exec
	s_cselect_b32 s55, 4, 1
	s_lshl_b32 s0, s54, 2
	s_sub_i32 s0, s6, s0
	s_ashr_i32 s1, s0, 31
	s_abs_i32 s0, s0
	s_mul_hi_u32 s26, s0, s51
	s_mul_i32 s26, s26, s50
	s_sub_i32 s0, s0, s26
	s_sub_i32 s26, s0, s50
	s_cmp_ge_u32 s0, s50
	s_cselect_b32 s0, s26, s0
	s_sub_i32 s26, s0, s50
	s_cmp_ge_u32 s0, s50
	s_cselect_b32 s0, s26, s0
	s_xor_b32 s0, s0, s1
	s_sub_i32 s56, s0, s1
	s_lshl_b32 s0, s10, 1
	s_lshl_b32 s36, s55, s0
	v_mov_b32_e32 v4, v241
	s_cmp_ge_i32 s56, s36
	v_readfirstlane_b32 s30, v4
	s_cbranch_scc1 .LBB0_174
	s_cmp_eq_u32 s100, 1
	s_cbranch_scc1 .LBB0_174
	s_ashr_i32 s59, s56, 31
	s_lshr_b32 s0, s59, 29
	s_add_i32 s27, s56, s0
	s_lshr_b32 s57, s36, 3
	s_and_b32 s0, s27, -8
	s_and_b32 s58, s36, 5
	s_sub_i32 s10, s56, s0
	s_or_b32 s60, s57, 1
	s_cmp_ge_i32 s10, s58
	s_mov_b64 s[0:1], -1
	s_mul_i32 s61, s60, s58
	s_cbranch_scc0 .LBB0_178
	s_sub_i32 s0, s10, s58
	s_mul_i32 s0, s0, s57
	s_add_i32 s26, s0, s61
	s_mov_b64 s[0:1], 0
